# attention A exp/PV section hand-scheduled: first PV MFMA after 8 exps, later exp groups under the MFMAs, V fragments double-buffered
# speedup vs baseline: 1.0041x; 1.0041x over previous
.LBB0_344:
	v_add3_u32 v14, s38, v185, v186
	v_add3_u32 v14, v14, v175, v176
	v_add_u32_e32 v248, v14, v187
	v_add_u32_e32 v249, v14, v190
	v_add_u32_e32 v250, v14, v191
	v_add_u32_e32 v251, v14, v192
	ds_read_b64_tr_b16 v[2:3], v248 offset:8192
	ds_read_b64_tr_b16 v[4:5], v248 offset:10240
	ds_read_b64_tr_b16 v[6:7], v249 offset:8192
	ds_read_b64_tr_b16 v[8:9], v249 offset:10240
	ds_read_b64_tr_b16 v[10:11], v250 offset:8192
	ds_read_b64_tr_b16 v[12:13], v250 offset:10240
	ds_read_b64_tr_b16 v[244:245], v251 offset:8192
	ds_read_b64_tr_b16 v[246:247], v251 offset:10240
	v_fma_f32 v96, v96, s43, -v151
	v_exp_f32_e32 v96, v96
	v_fma_f32 v97, v97, s43, -v151
	v_exp_f32_e32 v97, v97
	v_fma_f32 v98, v98, s43, -v151
	v_exp_f32_e32 v98, v98
	v_fma_f32 v99, v99, s43, -v151
	v_exp_f32_e32 v99, v99
	v_fma_f32 v100, v100, s43, -v151
	v_exp_f32_e32 v100, v100
	v_fma_f32 v101, v101, s43, -v151
	v_exp_f32_e32 v101, v101
	v_fma_f32 v102, v102, s43, -v151
	v_exp_f32_e32 v102, v102
	v_fma_f32 v103, v103, s43, -v151
	v_exp_f32_e32 v103, v103
	v_add_f32_e32 v0, v96, v97
	v_add_f32_e32 v14, v98, v99
	v_cvt_pk_bf16_f32 v96, v96, v97
	v_cvt_pk_bf16_f32 v97, v98, v99
	v_cvt_pk_bf16_f32 v98, v100, v101
	v_cvt_pk_bf16_f32 v99, v102, v103
	v_add_f32_e32 v15, v100, v101
	v_add_f32_e32 v0, v0, v102
	v_add_f32_e32 v14, v14, v103
	s_waitcnt lgkmcnt(6)
	v_mfma_f32_32x32x16_bf16 v[64:79], v[2:5], v[96:99], v[64:79]
	ds_read_b64_tr_b16 v[156:157], v248 offset:12288
	ds_read_b64_tr_b16 v[158:159], v248 offset:14336
	ds_read_b64_tr_b16 v[160:161], v249 offset:12288
	ds_read_b64_tr_b16 v[162:163], v249 offset:14336
	ds_read_b64_tr_b16 v[252:253], v250 offset:12288
	ds_read_b64_tr_b16 v[254:255], v250 offset:14336
	ds_read_b64_tr_b16 v[100:101], v251 offset:12288
	ds_read_b64_tr_b16 v[102:103], v251 offset:14336
	v_fma_f32 v104, v104, s43, -v151
	v_exp_f32_e32 v104, v104
	v_fma_f32 v105, v105, s43, -v151
	v_exp_f32_e32 v105, v105
	s_waitcnt lgkmcnt(12)
	v_mfma_f32_32x32x16_bf16 v[48:63], v[6:9], v[96:99], v[48:63]
	v_fma_f32 v106, v106, s43, -v151
	v_exp_f32_e32 v106, v106
	v_fma_f32 v107, v107, s43, -v151
	v_exp_f32_e32 v107, v107
	s_waitcnt lgkmcnt(10)
	v_mfma_f32_32x32x16_bf16 v[32:47], v[10:13], v[96:99], v[32:47]
	v_fma_f32 v108, v108, s43, -v151
	v_exp_f32_e32 v108, v108
	v_fma_f32 v109, v109, s43, -v151
	v_exp_f32_e32 v109, v109
	s_waitcnt lgkmcnt(8)
	v_mfma_f32_32x32x16_bf16 v[16:31], v[244:247], v[96:99], v[16:31]
	v_fma_f32 v110, v110, s43, -v151
	v_exp_f32_e32 v110, v110
	v_fma_f32 v111, v111, s43, -v151
	v_exp_f32_e32 v111, v111
	v_add_f32_e32 v0, v0, v104
	v_add_f32_e32 v14, v14, v105
	v_add_f32_e32 v15, v15, v106
	v_add_f32_e32 v0, v0, v107
	v_cvt_pk_bf16_f32 v104, v104, v105
	v_cvt_pk_bf16_f32 v105, v106, v107
	v_cvt_pk_bf16_f32 v106, v108, v109
	v_cvt_pk_bf16_f32 v107, v110, v111
	v_add_f32_e32 v14, v14, v108
	v_add_f32_e32 v15, v15, v109
	v_add_f32_e32 v0, v0, v110
	v_add_f32_e32 v14, v14, v111
	s_waitcnt lgkmcnt(6)
	v_mfma_f32_32x32x16_bf16 v[64:79], v[156:159], v[104:107], v[64:79]
	ds_read_b64_tr_b16 v[2:3], v248 offset:16384
	ds_read_b64_tr_b16 v[4:5], v248 offset:18432
	ds_read_b64_tr_b16 v[6:7], v249 offset:16384
	ds_read_b64_tr_b16 v[8:9], v249 offset:18432
	ds_read_b64_tr_b16 v[10:11], v250 offset:16384
	ds_read_b64_tr_b16 v[12:13], v250 offset:18432
	ds_read_b64_tr_b16 v[244:245], v251 offset:16384
	ds_read_b64_tr_b16 v[246:247], v251 offset:18432
	v_fma_f32 v80, v80, s43, -v151
	v_exp_f32_e32 v80, v80
	v_fma_f32 v81, v81, s43, -v151
	v_exp_f32_e32 v81, v81
	s_waitcnt lgkmcnt(12)
	v_mfma_f32_32x32x16_bf16 v[48:63], v[160:163], v[104:107], v[48:63]
	v_fma_f32 v82, v82, s43, -v151
	v_exp_f32_e32 v82, v82
	v_fma_f32 v83, v83, s43, -v151
	v_exp_f32_e32 v83, v83
	s_waitcnt lgkmcnt(10)
	v_mfma_f32_32x32x16_bf16 v[32:47], v[252:255], v[104:107], v[32:47]
	v_fma_f32 v84, v84, s43, -v151
	v_exp_f32_e32 v84, v84
	v_fma_f32 v85, v85, s43, -v151
	v_exp_f32_e32 v85, v85
	s_waitcnt lgkmcnt(8)
	v_mfma_f32_32x32x16_bf16 v[16:31], v[100:103], v[104:107], v[16:31]
	v_fma_f32 v86, v86, s43, -v151
	v_exp_f32_e32 v86, v86
	v_fma_f32 v87, v87, s43, -v151
	v_exp_f32_e32 v87, v87
	v_add_f32_e32 v0, v0, v80
	v_add_f32_e32 v14, v14, v81
	v_add_f32_e32 v15, v15, v82
	v_add_f32_e32 v0, v0, v83
	v_cvt_pk_bf16_f32 v80, v80, v81
	v_cvt_pk_bf16_f32 v81, v82, v83
	v_cvt_pk_bf16_f32 v82, v84, v85
	v_cvt_pk_bf16_f32 v83, v86, v87
	v_add_f32_e32 v14, v14, v84
	v_add_f32_e32 v15, v15, v85
	v_add_f32_e32 v0, v0, v86
	v_add_f32_e32 v14, v14, v87
	s_waitcnt lgkmcnt(6)
	v_mfma_f32_32x32x16_bf16 v[64:79], v[2:5], v[80:83], v[64:79]
	ds_read_b64_tr_b16 v[156:157], v248 offset:20480
	ds_read_b64_tr_b16 v[158:159], v248 offset:22528
	ds_read_b64_tr_b16 v[160:161], v249 offset:20480
	ds_read_b64_tr_b16 v[162:163], v249 offset:22528
	ds_read_b64_tr_b16 v[252:253], v250 offset:20480
	ds_read_b64_tr_b16 v[254:255], v250 offset:22528
	ds_read_b64_tr_b16 v[100:101], v251 offset:20480
	ds_read_b64_tr_b16 v[102:103], v251 offset:22528
	v_fma_f32 v88, v88, s43, -v151
	v_exp_f32_e32 v88, v88
	v_fma_f32 v89, v89, s43, -v151
	v_exp_f32_e32 v89, v89
	s_waitcnt lgkmcnt(12)
	v_mfma_f32_32x32x16_bf16 v[48:63], v[6:9], v[80:83], v[48:63]
	v_fma_f32 v90, v90, s43, -v151
	v_exp_f32_e32 v90, v90
	v_fma_f32 v91, v91, s43, -v151
	v_exp_f32_e32 v91, v91
	s_waitcnt lgkmcnt(10)
	v_mfma_f32_32x32x16_bf16 v[32:47], v[10:13], v[80:83], v[32:47]
	v_fma_f32 v92, v92, s43, -v151
	v_exp_f32_e32 v92, v92
	v_fma_f32 v93, v93, s43, -v151
	v_exp_f32_e32 v93, v93
	s_waitcnt lgkmcnt(8)
	v_mfma_f32_32x32x16_bf16 v[16:31], v[244:247], v[80:83], v[16:31]
	v_fma_f32 v94, v94, s43, -v151
	v_exp_f32_e32 v94, v94
	v_fma_f32 v95, v95, s43, -v151
	v_exp_f32_e32 v95, v95
	v_add_f32_e32 v0, v0, v88
	v_add_f32_e32 v14, v14, v89
	v_add_f32_e32 v15, v15, v90
	v_add_f32_e32 v0, v0, v91
	v_cvt_pk_bf16_f32 v88, v88, v89
	v_cvt_pk_bf16_f32 v89, v90, v91
	v_cvt_pk_bf16_f32 v90, v92, v93
	v_cvt_pk_bf16_f32 v91, v94, v95
	v_add_f32_e32 v14, v14, v92
	v_add_f32_e32 v15, v15, v93
	v_add_f32_e32 v0, v0, v94
	v_add_f32_e32 v14, v14, v95
	s_waitcnt lgkmcnt(6)
	v_mfma_f32_32x32x16_bf16 v[64:79], v[156:159], v[88:91], v[64:79]
	s_waitcnt lgkmcnt(4)
	v_mfma_f32_32x32x16_bf16 v[48:63], v[160:163], v[88:91], v[48:63]
	s_waitcnt lgkmcnt(2)
	v_mfma_f32_32x32x16_bf16 v[32:47], v[252:255], v[88:91], v[32:47]
	s_waitcnt lgkmcnt(0)
	v_mfma_f32_32x32x16_bf16 v[16:31], v[100:103], v[88:91], v[16:31]
	v_add_f32_e32 v0, v0, v14
	v_add_f32_e32 v150, v150, v15
	v_add_f32_e32 v150, v150, v0

.LBB0_362:
	v_add3_u32 v14, s28, v185, v186
	v_add3_u32 v14, v14, v175, v176
	v_add_u32_e32 v248, v14, v187
	v_add_u32_e32 v249, v14, v190
	v_add_u32_e32 v250, v14, v191
	v_add_u32_e32 v251, v14, v192
	ds_read_b64_tr_b16 v[2:3], v248 offset:8192
	ds_read_b64_tr_b16 v[4:5], v248 offset:10240
	ds_read_b64_tr_b16 v[6:7], v249 offset:8192
	ds_read_b64_tr_b16 v[8:9], v249 offset:10240
	ds_read_b64_tr_b16 v[10:11], v250 offset:8192
	ds_read_b64_tr_b16 v[12:13], v250 offset:10240
	ds_read_b64_tr_b16 v[244:245], v251 offset:8192
	ds_read_b64_tr_b16 v[246:247], v251 offset:10240
	v_fma_f32 v96, v96, s43, -v150
	v_exp_f32_e32 v96, v96
	v_fma_f32 v97, v97, s43, -v150
	v_exp_f32_e32 v97, v97
	v_fma_f32 v98, v98, s43, -v150
	v_exp_f32_e32 v98, v98
	v_fma_f32 v99, v99, s43, -v150
	v_exp_f32_e32 v99, v99
	v_fma_f32 v100, v100, s43, -v150
	v_exp_f32_e32 v100, v100
	v_fma_f32 v101, v101, s43, -v150
	v_exp_f32_e32 v101, v101
	v_fma_f32 v102, v102, s43, -v150
	v_exp_f32_e32 v102, v102
	v_fma_f32 v103, v103, s43, -v150
	v_exp_f32_e32 v103, v103
	v_add_f32_e32 v0, v96, v97
	v_add_f32_e32 v14, v98, v99
	v_cvt_pk_bf16_f32 v96, v96, v97
	v_cvt_pk_bf16_f32 v97, v98, v99
	v_cvt_pk_bf16_f32 v98, v100, v101
	v_cvt_pk_bf16_f32 v99, v102, v103
	v_add_f32_e32 v15, v100, v101
	v_add_f32_e32 v0, v0, v102
	v_add_f32_e32 v14, v14, v103
	s_waitcnt lgkmcnt(6)
	v_mfma_f32_32x32x16_bf16 v[16:31], v[2:5], v[96:99], v[16:31]
	ds_read_b64_tr_b16 v[156:157], v248 offset:12288
	ds_read_b64_tr_b16 v[158:159], v248 offset:14336
	ds_read_b64_tr_b16 v[160:161], v249 offset:12288
	ds_read_b64_tr_b16 v[162:163], v249 offset:14336
	ds_read_b64_tr_b16 v[252:253], v250 offset:12288
	ds_read_b64_tr_b16 v[254:255], v250 offset:14336
	ds_read_b64_tr_b16 v[100:101], v251 offset:12288
	ds_read_b64_tr_b16 v[102:103], v251 offset:14336
	v_fma_f32 v104, v104, s43, -v150
	v_exp_f32_e32 v104, v104
	v_fma_f32 v105, v105, s43, -v150
	v_exp_f32_e32 v105, v105
	s_waitcnt lgkmcnt(12)
	v_mfma_f32_32x32x16_bf16 v[32:47], v[6:9], v[96:99], v[32:47]
	v_fma_f32 v106, v106, s43, -v150
	v_exp_f32_e32 v106, v106
	v_fma_f32 v107, v107, s43, -v150
	v_exp_f32_e32 v107, v107
	s_waitcnt lgkmcnt(10)
	v_mfma_f32_32x32x16_bf16 v[48:63], v[10:13], v[96:99], v[48:63]
	v_fma_f32 v108, v108, s43, -v150
	v_exp_f32_e32 v108, v108
	v_fma_f32 v109, v109, s43, -v150
	v_exp_f32_e32 v109, v109
	s_waitcnt lgkmcnt(8)
	v_mfma_f32_32x32x16_bf16 v[64:79], v[244:247], v[96:99], v[64:79]
	v_fma_f32 v110, v110, s43, -v150
	v_exp_f32_e32 v110, v110
	v_fma_f32 v111, v111, s43, -v150
	v_exp_f32_e32 v111, v111
	v_add_f32_e32 v0, v0, v104
	v_add_f32_e32 v14, v14, v105
	v_add_f32_e32 v15, v15, v106
	v_add_f32_e32 v0, v0, v107
	v_cvt_pk_bf16_f32 v104, v104, v105
	v_cvt_pk_bf16_f32 v105, v106, v107
	v_cvt_pk_bf16_f32 v106, v108, v109
	v_cvt_pk_bf16_f32 v107, v110, v111
	v_add_f32_e32 v14, v14, v108
	v_add_f32_e32 v15, v15, v109
	v_add_f32_e32 v0, v0, v110
	v_add_f32_e32 v14, v14, v111
	s_waitcnt lgkmcnt(6)
	v_mfma_f32_32x32x16_bf16 v[16:31], v[156:159], v[104:107], v[16:31]
	ds_read_b64_tr_b16 v[2:3], v248 offset:16384
	ds_read_b64_tr_b16 v[4:5], v248 offset:18432
	ds_read_b64_tr_b16 v[6:7], v249 offset:16384
	ds_read_b64_tr_b16 v[8:9], v249 offset:18432
	ds_read_b64_tr_b16 v[10:11], v250 offset:16384
	ds_read_b64_tr_b16 v[12:13], v250 offset:18432
	ds_read_b64_tr_b16 v[244:245], v251 offset:16384
	ds_read_b64_tr_b16 v[246:247], v251 offset:18432
	v_fma_f32 v80, v80, s43, -v150
	v_exp_f32_e32 v80, v80
	v_fma_f32 v81, v81, s43, -v150
	v_exp_f32_e32 v81, v81
	s_waitcnt lgkmcnt(12)
	v_mfma_f32_32x32x16_bf16 v[32:47], v[160:163], v[104:107], v[32:47]
	v_fma_f32 v82, v82, s43, -v150
	v_exp_f32_e32 v82, v82
	v_fma_f32 v83, v83, s43, -v150
	v_exp_f32_e32 v83, v83
	s_waitcnt lgkmcnt(10)
	v_mfma_f32_32x32x16_bf16 v[48:63], v[252:255], v[104:107], v[48:63]
	v_fma_f32 v84, v84, s43, -v150
	v_exp_f32_e32 v84, v84
	v_fma_f32 v85, v85, s43, -v150
	v_exp_f32_e32 v85, v85
	s_waitcnt lgkmcnt(8)
	v_mfma_f32_32x32x16_bf16 v[64:79], v[100:103], v[104:107], v[64:79]
	v_fma_f32 v86, v86, s43, -v150
	v_exp_f32_e32 v86, v86
	v_fma_f32 v87, v87, s43, -v150
	v_exp_f32_e32 v87, v87
	v_add_f32_e32 v0, v0, v80
	v_add_f32_e32 v14, v14, v81
	v_add_f32_e32 v15, v15, v82
	v_add_f32_e32 v0, v0, v83
	v_cvt_pk_bf16_f32 v80, v80, v81
	v_cvt_pk_bf16_f32 v81, v82, v83
	v_cvt_pk_bf16_f32 v82, v84, v85
	v_cvt_pk_bf16_f32 v83, v86, v87
	v_add_f32_e32 v14, v14, v84
	v_add_f32_e32 v15, v15, v85
	v_add_f32_e32 v0, v0, v86
	v_add_f32_e32 v14, v14, v87
	s_waitcnt lgkmcnt(6)
	v_mfma_f32_32x32x16_bf16 v[16:31], v[2:5], v[80:83], v[16:31]
	ds_read_b64_tr_b16 v[156:157], v248 offset:20480
	ds_read_b64_tr_b16 v[158:159], v248 offset:22528
	ds_read_b64_tr_b16 v[160:161], v249 offset:20480
	ds_read_b64_tr_b16 v[162:163], v249 offset:22528
	ds_read_b64_tr_b16 v[252:253], v250 offset:20480
	ds_read_b64_tr_b16 v[254:255], v250 offset:22528
	ds_read_b64_tr_b16 v[100:101], v251 offset:20480
	ds_read_b64_tr_b16 v[102:103], v251 offset:22528
	v_fma_f32 v88, v88, s43, -v150
	v_exp_f32_e32 v88, v88
	v_fma_f32 v89, v89, s43, -v150
	v_exp_f32_e32 v89, v89
	s_waitcnt lgkmcnt(12)
	v_mfma_f32_32x32x16_bf16 v[32:47], v[6:9], v[80:83], v[32:47]
	v_fma_f32 v90, v90, s43, -v150
	v_exp_f32_e32 v90, v90
	v_fma_f32 v91, v91, s43, -v150
	v_exp_f32_e32 v91, v91
	s_waitcnt lgkmcnt(10)
	v_mfma_f32_32x32x16_bf16 v[48:63], v[10:13], v[80:83], v[48:63]
	v_fma_f32 v92, v92, s43, -v150
	v_exp_f32_e32 v92, v92
	v_fma_f32 v93, v93, s43, -v150
	v_exp_f32_e32 v93, v93
	s_waitcnt lgkmcnt(8)
	v_mfma_f32_32x32x16_bf16 v[64:79], v[244:247], v[80:83], v[64:79]
	v_fma_f32 v94, v94, s43, -v150
	v_exp_f32_e32 v94, v94
	v_fma_f32 v95, v95, s43, -v150
	v_exp_f32_e32 v95, v95
	v_add_f32_e32 v0, v0, v88
	v_add_f32_e32 v14, v14, v89
	v_add_f32_e32 v15, v15, v90
	v_add_f32_e32 v0, v0, v91
	v_cvt_pk_bf16_f32 v88, v88, v89
	v_cvt_pk_bf16_f32 v89, v90, v91
	v_cvt_pk_bf16_f32 v90, v92, v93
	v_cvt_pk_bf16_f32 v91, v94, v95
	v_add_f32_e32 v14, v14, v92
	v_add_f32_e32 v15, v15, v93
	v_add_f32_e32 v0, v0, v94
	v_add_f32_e32 v14, v14, v95
	s_waitcnt lgkmcnt(6)
	v_mfma_f32_32x32x16_bf16 v[16:31], v[156:159], v[88:91], v[16:31]
	s_waitcnt lgkmcnt(4)
	v_mfma_f32_32x32x16_bf16 v[32:47], v[160:163], v[88:91], v[32:47]
	s_waitcnt lgkmcnt(2)
	v_mfma_f32_32x32x16_bf16 v[48:63], v[252:255], v[88:91], v[48:63]
	s_waitcnt lgkmcnt(0)
	v_mfma_f32_32x32x16_bf16 v[64:79], v[100:103], v[88:91], v[64:79]
	v_add_f32_e32 v0, v0, v14
	v_add_f32_e32 v154, v154, v15
	v_add_f32_e32 v154, v154, v0
